# v42 + removed conservative vmcnt(0) at in-proj A epilogue start (WAW guard on side-job address regs)
# baseline (speedup 1.0000x reference)
;     __device__ __forceinline__ void side_issue(Side& s, int ui, int c, int wid, int lane) const {
;         s.row = (c * upc + ui) * 8 + wid;
;         if (MODE == 0 && s.row < xrows) { const f32x4* xr = (const f32x4*)(xs + (size_t)s.row * 1024) + lane;
; #pragma unroll
;             for (int j = 0; j < 4; ++j) s.v[j] = __builtin_nontemporal_load(xr + 64 * j); }
;     }
.LBB0_221:
	s_add_i32 s2, s27, s43
	s_lshl_b32 s2, s2, 3
	s_add_i32 s76, s2, s14
	s_cmp_lt_i32 s76, s95
	s_cselect_b64 s[80:81], -1, 0
	s_cmp_ge_i32 s76, s95
	s_cbranch_scc1 .LBB0_223
	s_ashr_i32 s77, s76, 31
	s_lshl_b64 s[38:39], s[76:77], 12
	v_lshl_add_u64 v[0:1], v[174:175], 0, s[38:39]
	global_load_dwordx4 v[12:15], v[0:1], off nt
	global_load_dwordx4 v[8:11], v[0:1], off offset:1024 nt
	global_load_dwordx4 v[4:7], v[0:1], off offset:2048 nt
	s_nop 0
	global_load_dwordx4 v[0:3], v[0:1], off offset:3072 nt
